# code placement: phase-1 GEMM loops (pp, QKRope, QKG, VT) back at the baseline's byte phase mod 8 (one 4-byte pad before the layer loop, one after phase 1)
# speedup vs baseline: 1.0080x; 1.0009x over previous
.LBB0_203:
	s_nop 0
	v_writelane_b32 v251, s90, 57
	v_mov_b32_e32 v189, 0
	v_mbcnt_hi_u32_b32 v207, -1, v51
	v_writelane_b32 v251, s91, 58
	v_writelane_b32 v251, s88, 59
	v_mov_b32_e32 v209, 0x358637bd
	v_mov_b32_e32 v250, 1
	v_writelane_b32 v251, s89, 60
	v_writelane_b32 v251, s66, 61
	v_mov_b32_e32 v213, 0xff800000
	v_mov_b64_e32 v[190:191], 0x200
	v_writelane_b32 v251, s67, 62
	v_mov_b64_e32 v[192:193], 0x1ff
	v_readlane_b32 s48, v251, 4
	v_readlane_b32 s60, v251, 16
	v_readlane_b32 s61, v251, 17
	v_readlane_b32 s62, v251, 18
	v_readlane_b32 s63, v251, 19
	s_mov_b64 s[24:25], s[60:61]
	s_mov_b64 s[26:27], s[62:63]
	s_add_u32 s0, s26, 0x4000000
	v_readlane_b32 s49, v251, 5
	v_readlane_b32 s50, v251, 6
	v_readlane_b32 s51, v251, 7
	v_readlane_b32 s52, v251, 8
	v_readlane_b32 s53, v251, 9
	v_readlane_b32 s54, v251, 10
	v_readlane_b32 s55, v251, 11
	v_readlane_b32 s56, v251, 12
	v_readlane_b32 s57, v251, 13
	v_readlane_b32 s58, v251, 14
	v_readlane_b32 s59, v251, 15
	v_writelane_b32 v251, s0, 63
	s_addc_u32 s0, s27, 0
	s_add_u32 s90, s26, 0x10000000
	s_addc_u32 s91, s27, 0
	s_add_u32 s92, s26, 0x1c000000
	s_addc_u32 s93, s27, 0
	v_writelane_b32 v252, s0, 0
	s_add_u32 s0, s26, 0x101000
	s_addc_u32 s1, s27, 0
	v_writelane_b32 v252, s0, 1
	v_readlane_b32 s18, v251, 2
	v_readlane_b32 s20, v251, 3
	v_writelane_b32 v252, s1, 2
	s_add_u32 s0, s26, 0x2e00000
	v_writelane_b32 v252, s0, 3
	s_addc_u32 s0, s27, 0
	v_writelane_b32 v252, s0, 4
	s_and_b32 s0, s18, 1
	s_add_u32 s22, s26, 0x1d000000
	s_addc_u32 s23, s27, 0
	s_cmpk_lt_i32 s18, 0x500
	v_writelane_b32 v252, s0, 5
	s_cselect_b64 s[0:1], -1, 0
	v_writelane_b32 v252, s0, 6
	s_ashr_i32 s2, s18, 31
	s_ashr_i32 s33, s3, 31
	v_writelane_b32 v252, s1, 7
	s_lshr_b32 s0, s2, 29
	s_add_i32 s0, s18, s0
	s_ashr_i32 s8, s0, 3
	s_and_b32 s0, s0, -8
	s_sub_i32 s9, s18, s0
	s_cmpk_lt_i32 s18, 0x600
	s_cselect_b64 s[0:1], -1, 0
	s_cmpk_lt_i32 s18, 0x200
	v_writelane_b32 v252, s0, 8
	s_cselect_b64 s[28:29], -1, 0
	s_lshl_b32 s10, s9, 6
	v_writelane_b32 v252, s1, 9
	s_add_u32 s0, s26, 0x200
	s_addc_u32 s1, s27, 0
	v_writelane_b32 v252, s0, 10
	v_mov_b64_e32 v[248:249], 0x500
	v_mov_b64_e32 v[210:211], 0x4ff
	v_writelane_b32 v252, s1, 11
	s_add_u32 s0, s26, 0x1000
	s_addc_u32 s1, s27, 0
	v_writelane_b32 v252, s0, 12
	v_mov_b32_e32 v212, 0x3e38aa3b
	v_mov_b64_e32 v[198:199], 0x600
	v_writelane_b32 v252, s1, 13
	s_add_u32 s0, s26, 0x1100
	s_addc_u32 s1, s27, 0
	v_writelane_b32 v252, s0, 14
	v_mov_b64_e32 v[200:201], 0x5ff
	v_mov_b32_e32 v214, 0x21c00
	v_writelane_b32 v252, s1, 15
	s_add_u32 s0, s26, 0x1200
	s_addc_u32 s1, s27, 0
	v_writelane_b32 v252, s0, 16
	s_mov_b64 s[62:63], 0x80
	s_mov_b64 s[88:89], 0x8000
	v_writelane_b32 v252, s1, 17
	s_add_u32 s0, s26, 0x1300
	s_addc_u32 s1, s27, 0
	v_writelane_b32 v252, s0, 18
	s_cmp_eq_u32 s94, 15
	s_nop 0
	v_writelane_b32 v252, s1, 19
	s_cselect_b64 s[0:1], -1, 0
	v_writelane_b32 v252, s0, 20
	s_cmp_eq_u32 s94, 14
	s_nop 0
	v_writelane_b32 v252, s1, 21
	s_cselect_b64 s[0:1], -1, 0
	v_writelane_b32 v252, s0, 22
	s_cmp_eq_u32 s94, 13
	s_nop 0
	v_writelane_b32 v252, s1, 23
	s_cselect_b64 s[0:1], -1, 0
	v_writelane_b32 v252, s0, 24
	s_cmp_eq_u32 s94, 12
	s_nop 0
	v_writelane_b32 v252, s1, 25
	s_cselect_b64 s[0:1], -1, 0
	v_writelane_b32 v252, s0, 26
	s_cmp_eq_u32 s94, 11
	s_nop 0
	v_writelane_b32 v252, s1, 27
	s_cselect_b64 s[0:1], -1, 0
	v_writelane_b32 v252, s0, 28
	s_cmp_eq_u32 s94, 10
	s_nop 0
	v_writelane_b32 v252, s1, 29
	s_cselect_b64 s[0:1], -1, 0
	v_writelane_b32 v252, s0, 30
	s_cmp_eq_u32 s94, 9
	s_nop 0
	v_writelane_b32 v252, s1, 31
	s_cselect_b64 s[0:1], -1, 0
	v_writelane_b32 v252, s0, 32
	s_cmp_eq_u32 s94, 8
	s_nop 0
	v_writelane_b32 v252, s1, 33
	s_cselect_b64 s[0:1], -1, 0
	v_writelane_b32 v252, s0, 34
	s_cmp_eq_u32 s94, 7
	s_nop 0
	v_writelane_b32 v252, s1, 35
	s_cselect_b64 s[0:1], -1, 0
	v_writelane_b32 v252, s0, 36
	s_cmp_eq_u32 s94, 6
	s_nop 0
	v_writelane_b32 v252, s1, 37
	s_cselect_b64 s[0:1], -1, 0
	v_writelane_b32 v252, s0, 38
	s_cmp_eq_u32 s94, 5
	s_nop 0
	v_writelane_b32 v252, s1, 39
	s_cselect_b64 s[0:1], -1, 0
	v_writelane_b32 v252, s0, 40
	s_cmp_eq_u32 s94, 4
	s_nop 0
	v_writelane_b32 v252, s1, 41
	s_cselect_b64 s[0:1], -1, 0
	v_writelane_b32 v252, s0, 42
	s_cmp_eq_u32 s94, 3
	s_nop 0
	v_writelane_b32 v252, s1, 43
	s_cselect_b64 s[0:1], -1, 0
	v_writelane_b32 v252, s0, 44
	s_cmp_eq_u32 s94, 2
	s_nop 0
	v_writelane_b32 v252, s1, 45
	s_cselect_b64 s[0:1], -1, 0
	v_writelane_b32 v252, s0, 46
	s_cmp_eq_u32 s94, 1
	s_nop 0
	v_writelane_b32 v252, s1, 47
	s_cselect_b64 s[0:1], -1, 0
	v_writelane_b32 v252, s0, 48
	s_cmp_eq_u32 s94, 0
	s_nop 0
	v_writelane_b32 v252, s1, 49
	s_cselect_b64 s[0:1], -1, 0
	v_writelane_b32 v252, s0, 50
	s_nop 1
	v_writelane_b32 v252, s1, 51
	s_lshl_b64 s[0:1], s[6:7], 2
	s_add_u32 s0, s26, s0
	s_addc_u32 s1, s27, s1
	s_add_u32 s6, s0, 0x1400
	s_addc_u32 s7, s1, 0
	v_writelane_b32 v252, s6, 52
	s_add_u32 s0, s0, 0x2400
	s_addc_u32 s1, s1, 0
	v_writelane_b32 v252, s7, 53
	v_writelane_b32 v252, s0, 54
	s_nop 1
	v_writelane_b32 v252, s1, 55
	s_add_u32 s0, s26, 0x3400
	s_addc_u32 s1, s27, 0
	v_writelane_b32 v252, s0, 56
	s_nop 1
	v_writelane_b32 v252, s1, 57
	s_add_u32 s0, s26, 0x3500
	s_addc_u32 s1, s27, 0
	v_writelane_b32 v252, s0, 58
	s_cmpk_lt_u32 s19, 0x100
	s_nop 0
	v_writelane_b32 v252, s1, 59
	s_cselect_b64 s[0:1], -1, 0
	v_writelane_b32 v252, s0, 60
	s_cmpk_lt_i32 s20, 0x100
	s_nop 0
	v_writelane_b32 v252, s1, 61
	s_cselect_b64 s[0:1], -1, 0
	v_writelane_b32 v252, s0, 62
	s_add_u32 s5, s26, 0x14000000
	s_nop 0
	v_writelane_b32 v252, s1, 63
	s_addc_u32 s0, s27, 0
	v_writelane_b32 v253, s0, 0
	s_lshr_b32 s0, s20, 1
	s_and_b32 s0, s0, 12
	s_bfe_u32 s1, s95, 0x20004
	s_or_b32 s6, s1, s0
	s_and_b32 s0, s95, 8
	v_writelane_b32 v253, s0, 1
	s_ashr_i32 s0, s20, 5
	s_ashr_i32 s1, s0, 31
	s_lshl_b32 s11, s6, 7
	s_lshl_b32 s6, s4, 4
	s_lshr_b32 s19, s19, 7
	v_writelane_b32 v253, s6, 2
	s_lshl_b64 s[6:7], s[0:1], 12
	s_lshl_b32 s30, s19, 6
	v_writelane_b32 v253, s6, 3
	s_add_u32 s1, s90, s11
	s_nop 0
	v_writelane_b32 v253, s7, 4
	v_writelane_b32 v253, s1, 5
	s_addc_u32 s1, s91, 0
	v_writelane_b32 v253, s1, 6
	s_lshl_b32 s0, s0, 2
	s_bfe_u32 s1, s20, 0x20003
	s_or_b32 s0, s1, s0
	s_ashr_i32 s1, s0, 31
	s_lshl_b64 s[6:7], s[0:1], 19
	s_add_u32 s0, s92, s6
	v_writelane_b32 v253, s0, 7
	s_addc_u32 s0, s93, s7
	v_writelane_b32 v253, s0, 8
	s_add_u32 s0, s22, s6
	v_writelane_b32 v253, s0, 9
	s_addc_u32 s0, s23, s7
	v_writelane_b32 v253, s0, 10
	s_add_u32 s0, s26, s11
	s_addc_u32 s1, s27, 0
	s_add_u32 s0, s0, 0x10000c00
	v_writelane_b32 v253, s0, 11
	s_addc_u32 s0, s1, 0
	v_writelane_b32 v253, s0, 12
	s_add_u32 s0, s24, s11
	v_writelane_b32 v253, s0, 13
	s_addc_u32 s0, s25, 0
	s_cmp_lt_i32 s9, 0
	s_movk_i32 s1, 0xa1
	v_writelane_b32 v253, s0, 14
	s_mul_i32 s0, s9, 0x41
	s_cselect_b32 s1, s1, 0xa0
	s_cselect_b32 s0, s0, s10
	s_mul_i32 s1, s9, s1
	s_movk_i32 s10, 0xc1
	s_cselect_b32 s10, s10, 0xc0
	s_add_i32 s1, s1, s8
	s_mul_hi_i32 s11, s1, 0x66666667
	s_lshr_b32 s12, s11, 31
	s_ashr_i32 s11, s11, 5
	s_add_i32 s11, s11, s12
	s_mul_i32 s12, s11, 0x50
	s_sub_i32 s1, s1, s12
	s_bfe_i32 s12, s1, 0x80000
	s_bfe_u32 s12, s12, 0x3000c
	s_mul_i32 s9, s9, s10
	s_add_i32 s12, s1, s12
	s_add_i32 s9, s9, s8
	s_and_b32 s13, s12, 0xf8
	s_mul_hi_i32 s10, s9, 0x2aaaaaab
	s_sub_i32 s1, s1, s13
	s_lshr_b32 s13, s10, 31
	s_ashr_i32 s10, s10, 4
	s_add_i32 s10, s10, s13
	s_mul_i32 s13, s10, 0x60
	s_sub_i32 s9, s9, s13
	s_bfe_i32 s13, s9, 0x80000
	s_bfe_u32 s13, s13, 0x3000c
	s_add_i32 s13, s9, s13
	s_add_i32 s0, s0, s8
	s_and_b32 s14, s13, 0xf8
	s_ashr_i32 s8, s0, 31
	s_sub_i32 s9, s9, s14
	s_lshr_b32 s14, s8, 22
	s_lshr_b32 s8, s8, 27
	s_add_i32 s14, s0, s14
	s_add_i32 s8, s0, s8
	s_and_b32 s15, s14, 0xfffffc00
	s_and_b32 s16, s8, 0xffe0
	s_sub_i32 s15, s0, s15
	s_sub_i32 s0, s0, s16
	s_bfe_i32 s16, s0, 0x80000
	s_bfe_u32 s16, s16, 0x3000c
	s_add_i32 s16, s0, s16
	s_and_b32 s17, s16, 0xf8
	s_sub_i32 s17, s0, s17
	s_lshl_b32 s0, s11, 3
	s_sext_i32_i8 s1, s1
	s_add_i32 s34, s0, s1
	s_bfe_i32 s1, s13, 0x80000
	s_lshl_b32 s0, s10, 3
	s_sext_i32_i16 s1, s1
	s_sext_i32_i8 s9, s9
	s_add_i32 s36, s0, s9
	s_ashr_i32 s0, s1, 3
	v_writelane_b32 v253, s0, 15
	s_lshr_b32 s0, s1, 3
	s_bfe_i64 s[0:1], s[0:1], 0x100000
	s_lshl_b64 s[0:1], s[0:1], 19
	v_writelane_b32 v253, s0, 16
	s_bfe_i32 s11, s12, 0x80000
	s_sext_i32_i16 s11, s11
	v_writelane_b32 v253, s1, 17
	s_ashr_i32 s0, s14, 10
	s_lshl_b32 s10, s0, 3
	s_sub_i32 s0, 4, s10
	s_min_u32 s12, s0, 8
	s_ashr_i32 s0, s8, 5
	s_bfe_i32 s1, s16, 0x80000
	s_lshl_b32 s0, s0, 3
	s_sext_i32_i16 s1, s1
	s_sext_i32_i8 s8, s17
	s_add_i32 s16, s0, s8
	s_ashr_i32 s0, s1, 3
	v_writelane_b32 v253, s0, 18
	s_ashr_i32 s8, s11, 3
	v_writelane_b32 v253, s8, 19
	s_lshr_b32 s8, s11, 3
	s_bfe_i64 s[8:9], s[8:9], 0x100000
	s_lshr_b32 s0, s1, 3
	s_lshl_b64 s[8:9], s[8:9], 19
	s_bfe_i64 s[0:1], s[0:1], 0x100000
	v_writelane_b32 v253, s8, 20
	s_ashr_i32 s37, s36, 31
	s_ashr_i32 s17, s16, 31
	v_writelane_b32 v253, s9, 21
	s_lshl_b64 s[8:9], s[0:1], 17
	v_writelane_b32 v253, s8, 22
	s_lshl_b64 s[0:1], s[0:1], 19
	s_ashr_i32 s35, s34, 31
	v_writelane_b32 v253, s9, 23
	v_writelane_b32 v253, s0, 24
	v_cvt_f32_ubyte0_e32 v1, s12
	v_cvt_f32_i32_e32 v0, s15
	v_writelane_b32 v253, s1, 25
	s_mov_b32 s0, s36
	v_writelane_b32 v253, s0, 26
	v_rcp_iflag_f32_e32 v2, v1
	s_nop 0
	v_writelane_b32 v253, s1, 27
	s_lshl_b64 s[0:1], s[36:37], 19
	v_writelane_b32 v253, s0, 28
	v_mul_f32_e32 v2, v0, v2
	v_trunc_f32_e32 v2, v2
	v_writelane_b32 v253, s1, 29
	s_lshl_b64 s[0:1], s[16:17], 17
	v_writelane_b32 v253, s0, 30
	v_fma_f32 v0, -v2, v1, v0
	s_nop 0
	v_writelane_b32 v253, s1, 31
	s_mov_b32 s0, s34
	v_writelane_b32 v253, s0, 32
	s_nop 1
	v_writelane_b32 v253, s1, 33
	s_lshl_b64 s[0:1], s[34:35], 19
	v_writelane_b32 v253, s0, 34
	s_nop 1
	v_writelane_b32 v253, s1, 35
	s_mov_b32 s0, s16
	v_writelane_b32 v253, s0, 36
	s_nop 1
	v_writelane_b32 v253, s1, 37
	s_lshl_b64 s[0:1], s[16:17], 19
	s_add_u32 s8, s24, s0
	v_writelane_b32 v253, s0, 38
	s_addc_u32 s9, s25, s1
	s_mov_b32 s24, 0x3f803f80
	v_writelane_b32 v253, s1, 39
	s_add_u32 s0, s8, 0x40000
	v_writelane_b32 v253, s8, 40
	s_addc_u32 s1, s9, 0
	s_nop 0
	v_writelane_b32 v253, s9, 41
	v_writelane_b32 v253, s0, 42
	s_nop 1
	v_writelane_b32 v253, s1, 43
	s_ashr_i32 s0, s15, 30
	s_or_b32 s8, s0, 1
	v_cmp_ge_f32_e64 s[0:1], |v0|, v1
	v_cvt_i32_f32_e32 v0, v2
	s_and_b64 s[0:1], s[0:1], exec
	s_cselect_b32 s0, s8, 0
	v_writelane_b32 v253, s28, 44
	v_readfirstlane_b32 s1, v0
	s_add_i32 s0, s1, s0
	s_mul_i32 s1, s0, s12
	s_sub_i32 s1, s15, s1
	s_sext_i32_i16 s1, s1
	v_writelane_b32 v253, s29, 45
	s_add_i32 s8, s10, s1
	s_sext_i32_i16 s1, s0
	v_writelane_b32 v253, s1, 46
	s_bfe_i64 s[0:1], s[0:1], 0x100000
	s_lshl_b64 s[0:1], s[0:1], 19
	v_writelane_b32 v253, s0, 47
	s_ashr_i32 s9, s8, 31
	v_cndmask_b32_e64 v208, 0, 1, s[28:29]
	v_writelane_b32 v253, s1, 48
	s_mov_b32 s0, s8
	v_writelane_b32 v253, s0, 49
	s_mov_b32 s29, 0
	s_mov_b32 s31, s29
	v_writelane_b32 v253, s1, 50
	s_lshl_b64 s[0:1], s[8:9], 19
	v_writelane_b32 v253, s0, 51
	s_mov_b64 s[14:15], s[22:23]
	s_movk_i32 s9, 0x60
	v_writelane_b32 v253, s1, 52
	s_add_u32 s0, s26, s6
	s_addc_u32 s1, s27, s7
	s_add_u32 s6, s0, 0x1c002000
	v_writelane_b32 v253, s6, 53
	s_addc_u32 s6, s1, 0
	s_add_u32 s0, s0, 0x1d002000
	v_writelane_b32 v253, s6, 54
	s_addc_u32 s1, s1, 0
	v_writelane_b32 v253, s0, 55
	s_bitcmp1_b32 s20, 0
	s_nop 0
	v_writelane_b32 v253, s1, 56
	v_writelane_b32 v253, s30, 57
	s_cselect_b64 s[0:1], -1, 0
	s_bitcmp1_b32 s3, 0
	v_writelane_b32 v253, s31, 58
	v_writelane_b32 v253, s0, 59
	s_nop 1
	v_writelane_b32 v253, s1, 60
	s_cselect_b64 s[0:1], -1, 0
	v_writelane_b32 v253, s0, 61
	s_nop 1
	v_writelane_b32 v253, s1, 62
	s_add_u32 s0, s26, 0x18000040
	s_addc_u32 s1, s27, 0
	v_writelane_b32 v253, s0, 63
	s_add_i32 s6, 0, 0x21400
	s_nop 0
	v_writelane_b32 v254, s1, 0
	s_sub_i32 s0, 0, s19
	v_writelane_b32 v254, s0, 1
	s_add_i32 s1, 0, 0x23fc0
	v_writelane_b32 v254, s1, 2
	s_add_i32 s1, 0, 0x23fc4
	v_writelane_b32 v254, s1, 3
	v_writelane_b32 v254, s6, 4
	s_mov_b32 s0, 0x800000
	s_mov_b32 s1, 0x41000000
	s_mov_b32 s6, s29
	v_writelane_b32 v254, s5, 5
	s_branch .LBB0_207

.LBB0_324:
	s_nop 0
	v_readlane_b32 s8, v254, 8
	s_or_b32 s28, s8, 2
	s_cmp_lt_i32 s28, s45
	s_cselect_b64 s[10:11], -1, 0
	s_and_b64 s[12:13], s[6:7], s[10:11]
	s_andn2_b64 vcc, exec, s[12:13]
	v_readlane_b32 s5, v254, 5
	s_cbranch_vccnz .LBB0_378
	s_waitcnt vmcnt(0)
	s_waitcnt vmcnt(0) lgkmcnt(0)
	s_barrier
	s_mov_b64 s[12:13], exec
	v_readlane_b32 s20, v251, 20
	v_readlane_b32 s21, v251, 21
	s_and_b64 s[20:21], s[12:13], s[20:21]
	s_mov_b64 exec, s[20:21]
	s_cbranch_execz .LBB0_377
	v_readlane_b32 s6, v254, 2
	s_waitcnt vmcnt(0) expcnt(0) lgkmcnt(0)
	s_nop 0
	v_mov_b32_e32 v0, s6
	ds_read_b32 v2, v0
	v_readlane_b32 s6, v254, 3
	s_waitcnt lgkmcnt(0)
	v_cmp_ne_u32_e32 vcc, 0, v2
	v_mov_b32_e32 v0, s6
	ds_read_b32 v0, v0
	s_cbranch_vccnz .LBB0_341
	v_readlane_b32 s30, v251, 0
	v_readlane_b32 s31, v251, 1
	s_load_dwordx2 s[20:21], s[30:31], 0x4
	s_mov_b32 s37, 1
	s_waitcnt lgkmcnt(0)
	s_mul_i32 s36, s20, s3
	s_mul_i32 s36, s36, s21
	s_branch .LBB0_329
